# layer-1 sample memory attention item (phase 8) ported to the streaming hand-written version
# speedup vs baseline: 1.0344x; 1.0344x over previous
.LBB0_1295:
	s_andn2_b64 vcc, exec, s[2:3]
	s_cbranch_vccnz .LBB0_1305
	v_and_b32_e32 v18, 63, v208
	v_lshrrev_b32_e32 v19, 6, v208
	v_and_b32_e32 v20, 3, v19
	v_lshrrev_b32_e32 v21, 2, v19
	v_and_b32_e32 v22, 15, v18
	v_lshrrev_b32_e32 v23, 4, v18
	v_lshlrev_b32_e32 v176, 2, v18
	v_xor_b32_e32 v238, 64, v176
	v_xor_b32_e32 v239, 0x80, v176
	s_and_b32 s2, s77, 0x7c
	s_and_b32 s26, s77, 3
	v_readfirstlane_b32 s6, v21
	v_add_u32_e32 v230, s2, v20
	v_or_b32_e32 v230, 0x2000, v230
	v_mul_u32_u24_e32 v231, 0x3800, v230
	s_lshl_b32 s3, s26, 8
	v_lshl_add_u32 v232, v22, 4, v231
	v_add_u32_e32 v232, s3, v232
	v_add_u32_e32 v232, 0x3000, v232
	global_load_dwordx4 v[160:163], v232, s[14:15]
	v_add_u32_e32 v232, 0x400, v232
	v_mov_b32_e32 v233, 0
	v_lshl_add_u64 v[244:245], s[14:15], 0, v[232:233]
	v_mul_u32_u24_e32 v231, 0x1400, v230
	v_lshl_add_u32 v232, v22, 4, v231
	v_add_u32_e32 v232, s3, v232
	v_add_u32_e32 v232, 0x2e351800, v232
	v_lshl_add_u64 v[246:247], s[96:97], 0, v[232:233]
	s_lshl_b32 s7, s2, 17
	s_lshl_b32 s8, s26, 9
	s_lshl_b32 s6, s6, 18
	s_add_u32 s7, s7, s8
	s_add_u32 s7, s7, s6
	s_add_u32 s7, s7, 0x1000000
	s_add_u32 s2, s70, s7
	s_addc_u32 s3, s71, 0
	s_add_u32 s4, s72, s7
	s_addc_u32 s5, s73, 0
	v_lshlrev_b32_e32 v24, 15, v23
	v_lshl_add_u32 v24, v22, 5, v24
	v_add_u32_e32 v25, 0x1000, v24
	v_add_u32_e32 v26, 0x2000, v24
	v_add_u32_e32 v27, 0x3000, v24
	v_add_u32_e32 v28, 0x4000, v24
	v_add_u32_e32 v29, 0x5000, v24
	v_add_u32_e32 v30, 0x6000, v24
	v_add_u32_e32 v31, 0x7000, v24
	v_mov_b32_e32 v16, 0xf149f2ca
	v_mov_b32_e32 v17, 0
	v_mov_b32_e32 v8, 0
	v_mov_b32_e32 v9, 0
	v_mov_b32_e32 v10, 0
	v_mov_b32_e32 v11, 0
	v_mov_b32_e32 v12, 0
	v_mov_b32_e32 v13, 0
	v_mov_b32_e32 v14, 0
	v_mov_b32_e32 v15, 0
	global_load_dwordx4 v[32:35], v24, s[2:3]
	global_load_dwordx4 v[36:39], v24, s[2:3] offset:16
	global_load_dwordx4 v[40:43], v24, s[2:3] offset:2048
	global_load_dwordx4 v[44:47], v24, s[2:3] offset:2064
	global_load_dwordx4 v[48:51], v25, s[2:3]
	global_load_dwordx4 v[52:55], v25, s[2:3] offset:16
	global_load_dwordx4 v[56:59], v25, s[2:3] offset:2048
	global_load_dwordx4 v[60:63], v25, s[2:3] offset:2064
	global_load_dwordx4 v[64:67], v26, s[2:3]
	global_load_dwordx4 v[68:71], v26, s[2:3] offset:16
	global_load_dwordx4 v[72:75], v26, s[2:3] offset:2048
	global_load_dwordx4 v[76:79], v26, s[2:3] offset:2064
	global_load_dwordx4 v[80:83], v27, s[2:3]
	global_load_dwordx4 v[84:87], v27, s[2:3] offset:16
	global_load_dwordx4 v[88:91], v27, s[2:3] offset:2048
	global_load_dwordx4 v[92:95], v27, s[2:3] offset:2064
	global_load_dwordx4 v[96:99], v28, s[2:3]
	global_load_dwordx4 v[100:103], v28, s[2:3] offset:16
	global_load_dwordx4 v[104:107], v28, s[2:3] offset:2048
	global_load_dwordx4 v[108:111], v28, s[2:3] offset:2064
	global_load_dwordx4 v[112:115], v29, s[2:3]
	global_load_dwordx4 v[116:119], v29, s[2:3] offset:16
	global_load_dwordx4 v[120:123], v29, s[2:3] offset:2048
	global_load_dwordx4 v[124:127], v29, s[2:3] offset:2064
	global_load_dwordx4 v[128:131], v30, s[2:3]
	global_load_dwordx4 v[132:135], v30, s[2:3] offset:16
	global_load_dwordx4 v[136:139], v30, s[2:3] offset:2048
	global_load_dwordx4 v[140:143], v30, s[2:3] offset:2064
	global_load_dwordx4 v[144:147], v31, s[2:3]
	global_load_dwordx4 v[148:151], v31, s[2:3] offset:16
	global_load_dwordx4 v[152:155], v31, s[2:3] offset:2048
	global_load_dwordx4 v[156:159], v31, s[2:3] offset:2064
	s_waitcnt vmcnt(32)
	v_lshlrev_b32_e32 v0, 16, v160
	v_and_b32_e32 v1, 0xffff0000, v160
	v_lshlrev_b32_e32 v2, 16, v161
	v_and_b32_e32 v3, 0xffff0000, v161
	v_lshlrev_b32_e32 v4, 16, v162
	v_and_b32_e32 v5, 0xffff0000, v162
	v_lshlrev_b32_e32 v6, 16, v163
	v_and_b32_e32 v7, 0xffff0000, v163
	s_waitcnt vmcnt(30)
	v_mul_f32_e32 v160, v32, v0
	v_fmac_f32_e32 v160, v33, v1
	v_fmac_f32_e32 v160, v34, v2
	v_fmac_f32_e32 v160, v35, v3
	v_fmac_f32_e32 v160, v36, v4
	v_fmac_f32_e32 v160, v37, v5
	v_fmac_f32_e32 v160, v38, v6
	v_fmac_f32_e32 v160, v39, v7
	global_load_dwordx4 v[32:35], v24, s[4:5]
	global_load_dwordx4 v[36:39], v24, s[4:5] offset:16
	s_waitcnt vmcnt(30)
	v_mul_f32_e32 v161, v40, v0
	v_fmac_f32_e32 v161, v41, v1
	v_fmac_f32_e32 v161, v42, v2
	v_fmac_f32_e32 v161, v43, v3
	v_fmac_f32_e32 v161, v44, v4
	v_fmac_f32_e32 v161, v45, v5
	v_fmac_f32_e32 v161, v46, v6
	v_fmac_f32_e32 v161, v47, v7
	global_load_dwordx4 v[40:43], v24, s[4:5] offset:2048
	global_load_dwordx4 v[44:47], v24, s[4:5] offset:2064
	s_waitcnt vmcnt(30)
	v_mul_f32_e32 v162, v48, v0
	v_fmac_f32_e32 v162, v49, v1
	v_fmac_f32_e32 v162, v50, v2
	v_fmac_f32_e32 v162, v51, v3
	v_fmac_f32_e32 v162, v52, v4
	v_fmac_f32_e32 v162, v53, v5
	v_fmac_f32_e32 v162, v54, v6
	v_fmac_f32_e32 v162, v55, v7
	global_load_dwordx4 v[48:51], v25, s[4:5]
	global_load_dwordx4 v[52:55], v25, s[4:5] offset:16
	s_waitcnt vmcnt(30)
	v_mul_f32_e32 v163, v56, v0
	v_fmac_f32_e32 v163, v57, v1
	v_fmac_f32_e32 v163, v58, v2
	v_fmac_f32_e32 v163, v59, v3
	v_fmac_f32_e32 v163, v60, v4
	v_fmac_f32_e32 v163, v61, v5
	v_fmac_f32_e32 v163, v62, v6
	v_fmac_f32_e32 v163, v63, v7
	global_load_dwordx4 v[56:59], v25, s[4:5] offset:2048
	global_load_dwordx4 v[60:63], v25, s[4:5] offset:2064
	s_waitcnt vmcnt(30)
	v_mul_f32_e32 v164, v64, v0
	v_fmac_f32_e32 v164, v65, v1
	v_fmac_f32_e32 v164, v66, v2
	v_fmac_f32_e32 v164, v67, v3
	v_fmac_f32_e32 v164, v68, v4
	v_fmac_f32_e32 v164, v69, v5
	v_fmac_f32_e32 v164, v70, v6
	v_fmac_f32_e32 v164, v71, v7
	global_load_dwordx4 v[64:67], v26, s[4:5]
	global_load_dwordx4 v[68:71], v26, s[4:5] offset:16
	s_waitcnt vmcnt(30)
	v_mul_f32_e32 v165, v72, v0
	v_fmac_f32_e32 v165, v73, v1
	v_fmac_f32_e32 v165, v74, v2
	v_fmac_f32_e32 v165, v75, v3
	v_fmac_f32_e32 v165, v76, v4
	v_fmac_f32_e32 v165, v77, v5
	v_fmac_f32_e32 v165, v78, v6
	v_fmac_f32_e32 v165, v79, v7
	global_load_dwordx4 v[72:75], v26, s[4:5] offset:2048
	global_load_dwordx4 v[76:79], v26, s[4:5] offset:2064
	s_waitcnt vmcnt(30)
	v_mul_f32_e32 v166, v80, v0
	v_fmac_f32_e32 v166, v81, v1
	v_fmac_f32_e32 v166, v82, v2
	v_fmac_f32_e32 v166, v83, v3
	v_fmac_f32_e32 v166, v84, v4
	v_fmac_f32_e32 v166, v85, v5
	v_fmac_f32_e32 v166, v86, v6
	v_fmac_f32_e32 v166, v87, v7
	global_load_dwordx4 v[80:83], v27, s[4:5]
	global_load_dwordx4 v[84:87], v27, s[4:5] offset:16
	s_waitcnt vmcnt(30)
	v_mul_f32_e32 v167, v88, v0
	v_fmac_f32_e32 v167, v89, v1
	v_fmac_f32_e32 v167, v90, v2
	v_fmac_f32_e32 v167, v91, v3
	v_fmac_f32_e32 v167, v92, v4
	v_fmac_f32_e32 v167, v93, v5
	v_fmac_f32_e32 v167, v94, v6
	v_fmac_f32_e32 v167, v95, v7
	global_load_dwordx4 v[88:91], v27, s[4:5] offset:2048
	global_load_dwordx4 v[92:95], v27, s[4:5] offset:2064
	s_waitcnt vmcnt(30)
	v_mul_f32_e32 v168, v96, v0
	v_fmac_f32_e32 v168, v97, v1
	v_fmac_f32_e32 v168, v98, v2
	v_fmac_f32_e32 v168, v99, v3
	v_fmac_f32_e32 v168, v100, v4
	v_fmac_f32_e32 v168, v101, v5
	v_fmac_f32_e32 v168, v102, v6
	v_fmac_f32_e32 v168, v103, v7
	global_load_dwordx4 v[96:99], v28, s[4:5]
	global_load_dwordx4 v[100:103], v28, s[4:5] offset:16
	s_waitcnt vmcnt(30)
	v_mul_f32_e32 v169, v104, v0
	v_fmac_f32_e32 v169, v105, v1
	v_fmac_f32_e32 v169, v106, v2
	v_fmac_f32_e32 v169, v107, v3
	v_fmac_f32_e32 v169, v108, v4
	v_fmac_f32_e32 v169, v109, v5
	v_fmac_f32_e32 v169, v110, v6
	v_fmac_f32_e32 v169, v111, v7
	global_load_dwordx4 v[104:107], v28, s[4:5] offset:2048
	global_load_dwordx4 v[108:111], v28, s[4:5] offset:2064
	s_waitcnt vmcnt(30)
	v_mul_f32_e32 v170, v112, v0
	v_fmac_f32_e32 v170, v113, v1
	v_fmac_f32_e32 v170, v114, v2
	v_fmac_f32_e32 v170, v115, v3
	v_fmac_f32_e32 v170, v116, v4
	v_fmac_f32_e32 v170, v117, v5
	v_fmac_f32_e32 v170, v118, v6
	v_fmac_f32_e32 v170, v119, v7
	global_load_dwordx4 v[112:115], v29, s[4:5]
	global_load_dwordx4 v[116:119], v29, s[4:5] offset:16
	s_waitcnt vmcnt(30)
	v_mul_f32_e32 v171, v120, v0
	v_fmac_f32_e32 v171, v121, v1
	v_fmac_f32_e32 v171, v122, v2
	v_fmac_f32_e32 v171, v123, v3
	v_fmac_f32_e32 v171, v124, v4
	v_fmac_f32_e32 v171, v125, v5
	v_fmac_f32_e32 v171, v126, v6
	v_fmac_f32_e32 v171, v127, v7
	global_load_dwordx4 v[120:123], v29, s[4:5] offset:2048
	global_load_dwordx4 v[124:127], v29, s[4:5] offset:2064
	s_waitcnt vmcnt(30)
	v_mul_f32_e32 v172, v128, v0
	v_fmac_f32_e32 v172, v129, v1
	v_fmac_f32_e32 v172, v130, v2
	v_fmac_f32_e32 v172, v131, v3
	v_fmac_f32_e32 v172, v132, v4
	v_fmac_f32_e32 v172, v133, v5
	v_fmac_f32_e32 v172, v134, v6
	v_fmac_f32_e32 v172, v135, v7
	global_load_dwordx4 v[128:131], v30, s[4:5]
	global_load_dwordx4 v[132:135], v30, s[4:5] offset:16
	s_waitcnt vmcnt(30)
	v_mul_f32_e32 v173, v136, v0
	v_fmac_f32_e32 v173, v137, v1
	v_fmac_f32_e32 v173, v138, v2
	v_fmac_f32_e32 v173, v139, v3
	v_fmac_f32_e32 v173, v140, v4
	v_fmac_f32_e32 v173, v141, v5
	v_fmac_f32_e32 v173, v142, v6
	v_fmac_f32_e32 v173, v143, v7
	global_load_dwordx4 v[136:139], v30, s[4:5] offset:2048
	global_load_dwordx4 v[140:143], v30, s[4:5] offset:2064
	s_waitcnt vmcnt(30)
	v_mul_f32_e32 v174, v144, v0
	v_fmac_f32_e32 v174, v145, v1
	v_fmac_f32_e32 v174, v146, v2
	v_fmac_f32_e32 v174, v147, v3
	v_fmac_f32_e32 v174, v148, v4
	v_fmac_f32_e32 v174, v149, v5
	v_fmac_f32_e32 v174, v150, v6
	v_fmac_f32_e32 v174, v151, v7
	global_load_dwordx4 v[144:147], v31, s[4:5]
	global_load_dwordx4 v[148:151], v31, s[4:5] offset:16
	s_waitcnt vmcnt(30)
	v_mul_f32_e32 v175, v152, v0
	v_fmac_f32_e32 v175, v153, v1
	v_fmac_f32_e32 v175, v154, v2
	v_fmac_f32_e32 v175, v155, v3
	v_fmac_f32_e32 v175, v156, v4
	v_fmac_f32_e32 v175, v157, v5
	v_fmac_f32_e32 v175, v158, v6
	v_fmac_f32_e32 v175, v159, v7
	global_load_dwordx4 v[152:155], v31, s[4:5] offset:2048
	global_load_dwordx4 v[156:159], v31, s[4:5] offset:2064
	v_add_f32_dpp v160, v160, v160 row_ror:8 row_mask:0xf bank_mask:0x3
	v_add_f32_dpp v160, v168, v168 row_ror:8 row_mask:0xf bank_mask:0xc
	v_add_f32_dpp v161, v161, v161 row_ror:8 row_mask:0xf bank_mask:0x3
	v_add_f32_dpp v161, v169, v169 row_ror:8 row_mask:0xf bank_mask:0xc
	v_add_f32_dpp v162, v162, v162 row_ror:8 row_mask:0xf bank_mask:0x3
	v_add_f32_dpp v162, v170, v170 row_ror:8 row_mask:0xf bank_mask:0xc
	v_add_f32_dpp v163, v163, v163 row_ror:8 row_mask:0xf bank_mask:0x3
	v_add_f32_dpp v163, v171, v171 row_ror:8 row_mask:0xf bank_mask:0xc
	v_add_f32_dpp v164, v164, v164 row_ror:8 row_mask:0xf bank_mask:0x3
	v_add_f32_dpp v164, v172, v172 row_ror:8 row_mask:0xf bank_mask:0xc
	v_add_f32_dpp v165, v165, v165 row_ror:8 row_mask:0xf bank_mask:0x3
	v_add_f32_dpp v165, v173, v173 row_ror:8 row_mask:0xf bank_mask:0xc
	v_add_f32_dpp v166, v166, v166 row_ror:8 row_mask:0xf bank_mask:0x3
	v_add_f32_dpp v166, v174, v174 row_ror:8 row_mask:0xf bank_mask:0xc
	v_add_f32_dpp v167, v167, v167 row_ror:8 row_mask:0xf bank_mask:0x3
	v_add_f32_dpp v167, v175, v175 row_ror:8 row_mask:0xf bank_mask:0xc
	v_add_f32_dpp v160, v160, v160 row_shl:4 row_mask:0xf bank_mask:0x5
	v_add_f32_dpp v160, v164, v164 row_shr:4 row_mask:0xf bank_mask:0xa
	v_add_f32_dpp v161, v161, v161 row_shl:4 row_mask:0xf bank_mask:0x5
	v_add_f32_dpp v161, v165, v165 row_shr:4 row_mask:0xf bank_mask:0xa
	v_add_f32_dpp v162, v162, v162 row_shl:4 row_mask:0xf bank_mask:0x5
	v_add_f32_dpp v162, v166, v166 row_shr:4 row_mask:0xf bank_mask:0xa
	v_add_f32_dpp v163, v163, v163 row_shl:4 row_mask:0xf bank_mask:0x5
	v_add_f32_dpp v163, v167, v167 row_shr:4 row_mask:0xf bank_mask:0xa
	v_and_b32_e32 v176, 2, v18
	v_cmp_ne_u32_e32 vcc, 0, v176
	v_add_f32_dpp v230, v160, v160 quad_perm:[2,3,0,1] row_mask:0xf bank_mask:0xf
	v_add_f32_dpp v231, v162, v162 quad_perm:[2,3,0,1] row_mask:0xf bank_mask:0xf
	v_add_f32_dpp v232, v161, v161 quad_perm:[2,3,0,1] row_mask:0xf bank_mask:0xf
	v_add_f32_dpp v233, v163, v163 quad_perm:[2,3,0,1] row_mask:0xf bank_mask:0xf
	v_cndmask_b32_e32 v230, v230, v231, vcc
	v_cndmask_b32_e32 v232, v232, v233, vcc
	v_and_b32_e32 v176, 1, v18
	v_cmp_ne_u32_e32 vcc, 0, v176
	v_add_f32_dpp v231, v230, v230 quad_perm:[1,0,3,2] row_mask:0xf bank_mask:0xf
	v_add_f32_dpp v233, v232, v232 quad_perm:[1,0,3,2] row_mask:0xf bank_mask:0xf
	s_nop 1
	v_cndmask_b32_e32 v241, v231, v233, vcc
	s_nop 1
	v_max_f32_dpp v242, v241, v241 row_ror:8 row_mask:0xf bank_mask:0xf
	s_nop 1
	v_max_f32_dpp v242, v242, v242 row_ror:4 row_mask:0xf bank_mask:0xf
	s_nop 1
	v_max_f32_dpp v242, v242, v242 row_ror:2 row_mask:0xf bank_mask:0xf
	s_nop 1
	v_max_f32_dpp v242, v242, v242 row_ror:1 row_mask:0xf bank_mask:0xf
	ds_bpermute_b32 v234, v238, v242
	s_waitcnt lgkmcnt(0)
	v_max_f32_e32 v242, v242, v234
	ds_bpermute_b32 v234, v239, v242
	s_waitcnt lgkmcnt(0)
	v_max_f32_e32 v242, v242, v234
	v_max_f32_e32 v242, v16, v242
	v_sub_f32_e32 v243, v16, v242
	v_sub_f32_e32 v240, v241, v242
	v_mul_f32_e32 v243, 0x3fb8aa3b, v243
	v_mul_f32_e32 v240, 0x3fb8aa3b, v240
	v_exp_f32_e32 v243, v243
	v_exp_f32_e32 v240, v240
	v_mov_b32_e32 v16, v242
	s_nop 0
	s_nop 1
	v_add_f32_dpp v235, v240, v240 row_ror:8 row_mask:0xf bank_mask:0xf
	s_nop 1
	v_add_f32_dpp v235, v235, v235 row_ror:4 row_mask:0xf bank_mask:0xf
	s_nop 1
	v_add_f32_dpp v235, v235, v235 row_ror:2 row_mask:0xf bank_mask:0xf
	s_nop 1
	v_add_f32_dpp v235, v235, v235 row_ror:1 row_mask:0xf bank_mask:0xf
	ds_bpermute_b32 v234, v238, v235
	s_waitcnt lgkmcnt(0)
	v_add_f32_e32 v235, v235, v234
	ds_bpermute_b32 v234, v239, v235
	s_waitcnt lgkmcnt(0)
	v_add_f32_e32 v235, v235, v234
	v_fma_f32 v17, v17, v243, v235
	v_mul_f32_e32 v8, v8, v243
	v_mul_f32_e32 v9, v9, v243
	v_mul_f32_e32 v10, v10, v243
	v_mul_f32_e32 v11, v11, v243
	v_mul_f32_e32 v12, v12, v243
	v_mul_f32_e32 v13, v13, v243
	v_mul_f32_e32 v14, v14, v243
	v_mul_f32_e32 v15, v15, v243
	s_add_u32 s2, s2, 0x20000
	s_addc_u32 s3, s3, 0
	s_add_u32 s4, s4, 0x20000
	s_addc_u32 s5, s5, 0
	s_waitcnt vmcnt(30)
	v_fmac_f32_dpp v8, v240, v32 row_newbcast:0 row_mask:0xf bank_mask:0xf
	v_fmac_f32_dpp v9, v240, v33 row_newbcast:0 row_mask:0xf bank_mask:0xf
	v_fmac_f32_dpp v10, v240, v34 row_newbcast:0 row_mask:0xf bank_mask:0xf
	v_fmac_f32_dpp v11, v240, v35 row_newbcast:0 row_mask:0xf bank_mask:0xf
	v_fmac_f32_dpp v12, v240, v36 row_newbcast:0 row_mask:0xf bank_mask:0xf
	v_fmac_f32_dpp v13, v240, v37 row_newbcast:0 row_mask:0xf bank_mask:0xf
	v_fmac_f32_dpp v14, v240, v38 row_newbcast:0 row_mask:0xf bank_mask:0xf
	v_fmac_f32_dpp v15, v240, v39 row_newbcast:0 row_mask:0xf bank_mask:0xf
	global_load_dwordx4 v[32:35], v24, s[2:3]
	global_load_dwordx4 v[36:39], v24, s[2:3] offset:16
	s_waitcnt vmcnt(30)
	v_fmac_f32_dpp v8, v240, v40 row_newbcast:1 row_mask:0xf bank_mask:0xf
	v_fmac_f32_dpp v9, v240, v41 row_newbcast:1 row_mask:0xf bank_mask:0xf
	v_fmac_f32_dpp v10, v240, v42 row_newbcast:1 row_mask:0xf bank_mask:0xf
	v_fmac_f32_dpp v11, v240, v43 row_newbcast:1 row_mask:0xf bank_mask:0xf
	v_fmac_f32_dpp v12, v240, v44 row_newbcast:1 row_mask:0xf bank_mask:0xf
	v_fmac_f32_dpp v13, v240, v45 row_newbcast:1 row_mask:0xf bank_mask:0xf
	v_fmac_f32_dpp v14, v240, v46 row_newbcast:1 row_mask:0xf bank_mask:0xf
	v_fmac_f32_dpp v15, v240, v47 row_newbcast:1 row_mask:0xf bank_mask:0xf
	global_load_dwordx4 v[40:43], v24, s[2:3] offset:2048
	global_load_dwordx4 v[44:47], v24, s[2:3] offset:2064
	s_waitcnt vmcnt(30)
	v_fmac_f32_dpp v8, v240, v48 row_newbcast:2 row_mask:0xf bank_mask:0xf
	v_fmac_f32_dpp v9, v240, v49 row_newbcast:2 row_mask:0xf bank_mask:0xf
	v_fmac_f32_dpp v10, v240, v50 row_newbcast:2 row_mask:0xf bank_mask:0xf
	v_fmac_f32_dpp v11, v240, v51 row_newbcast:2 row_mask:0xf bank_mask:0xf
	v_fmac_f32_dpp v12, v240, v52 row_newbcast:2 row_mask:0xf bank_mask:0xf
	v_fmac_f32_dpp v13, v240, v53 row_newbcast:2 row_mask:0xf bank_mask:0xf
	v_fmac_f32_dpp v14, v240, v54 row_newbcast:2 row_mask:0xf bank_mask:0xf
	v_fmac_f32_dpp v15, v240, v55 row_newbcast:2 row_mask:0xf bank_mask:0xf
	global_load_dwordx4 v[48:51], v25, s[2:3]
	global_load_dwordx4 v[52:55], v25, s[2:3] offset:16
	s_waitcnt vmcnt(30)
	v_fmac_f32_dpp v8, v240, v56 row_newbcast:3 row_mask:0xf bank_mask:0xf
	v_fmac_f32_dpp v9, v240, v57 row_newbcast:3 row_mask:0xf bank_mask:0xf
	v_fmac_f32_dpp v10, v240, v58 row_newbcast:3 row_mask:0xf bank_mask:0xf
	v_fmac_f32_dpp v11, v240, v59 row_newbcast:3 row_mask:0xf bank_mask:0xf
	v_fmac_f32_dpp v12, v240, v60 row_newbcast:3 row_mask:0xf bank_mask:0xf
	v_fmac_f32_dpp v13, v240, v61 row_newbcast:3 row_mask:0xf bank_mask:0xf
	v_fmac_f32_dpp v14, v240, v62 row_newbcast:3 row_mask:0xf bank_mask:0xf
	v_fmac_f32_dpp v15, v240, v63 row_newbcast:3 row_mask:0xf bank_mask:0xf
	global_load_dwordx4 v[56:59], v25, s[2:3] offset:2048
	global_load_dwordx4 v[60:63], v25, s[2:3] offset:2064
	s_waitcnt vmcnt(30)
	v_fmac_f32_dpp v8, v240, v64 row_newbcast:4 row_mask:0xf bank_mask:0xf
	v_fmac_f32_dpp v9, v240, v65 row_newbcast:4 row_mask:0xf bank_mask:0xf
	v_fmac_f32_dpp v10, v240, v66 row_newbcast:4 row_mask:0xf bank_mask:0xf
	v_fmac_f32_dpp v11, v240, v67 row_newbcast:4 row_mask:0xf bank_mask:0xf
	v_fmac_f32_dpp v12, v240, v68 row_newbcast:4 row_mask:0xf bank_mask:0xf
	v_fmac_f32_dpp v13, v240, v69 row_newbcast:4 row_mask:0xf bank_mask:0xf
	v_fmac_f32_dpp v14, v240, v70 row_newbcast:4 row_mask:0xf bank_mask:0xf
	v_fmac_f32_dpp v15, v240, v71 row_newbcast:4 row_mask:0xf bank_mask:0xf
	global_load_dwordx4 v[64:67], v26, s[2:3]
	global_load_dwordx4 v[68:71], v26, s[2:3] offset:16
	s_waitcnt vmcnt(30)
	v_fmac_f32_dpp v8, v240, v72 row_newbcast:5 row_mask:0xf bank_mask:0xf
	v_fmac_f32_dpp v9, v240, v73 row_newbcast:5 row_mask:0xf bank_mask:0xf
	v_fmac_f32_dpp v10, v240, v74 row_newbcast:5 row_mask:0xf bank_mask:0xf
	v_fmac_f32_dpp v11, v240, v75 row_newbcast:5 row_mask:0xf bank_mask:0xf
	v_fmac_f32_dpp v12, v240, v76 row_newbcast:5 row_mask:0xf bank_mask:0xf
	v_fmac_f32_dpp v13, v240, v77 row_newbcast:5 row_mask:0xf bank_mask:0xf
	v_fmac_f32_dpp v14, v240, v78 row_newbcast:5 row_mask:0xf bank_mask:0xf
	v_fmac_f32_dpp v15, v240, v79 row_newbcast:5 row_mask:0xf bank_mask:0xf
	global_load_dwordx4 v[72:75], v26, s[2:3] offset:2048
	global_load_dwordx4 v[76:79], v26, s[2:3] offset:2064
	s_waitcnt vmcnt(30)
	v_fmac_f32_dpp v8, v240, v80 row_newbcast:6 row_mask:0xf bank_mask:0xf
	v_fmac_f32_dpp v9, v240, v81 row_newbcast:6 row_mask:0xf bank_mask:0xf
	v_fmac_f32_dpp v10, v240, v82 row_newbcast:6 row_mask:0xf bank_mask:0xf
	v_fmac_f32_dpp v11, v240, v83 row_newbcast:6 row_mask:0xf bank_mask:0xf
	v_fmac_f32_dpp v12, v240, v84 row_newbcast:6 row_mask:0xf bank_mask:0xf
	v_fmac_f32_dpp v13, v240, v85 row_newbcast:6 row_mask:0xf bank_mask:0xf
	v_fmac_f32_dpp v14, v240, v86 row_newbcast:6 row_mask:0xf bank_mask:0xf
	v_fmac_f32_dpp v15, v240, v87 row_newbcast:6 row_mask:0xf bank_mask:0xf
	global_load_dwordx4 v[80:83], v27, s[2:3]
	global_load_dwordx4 v[84:87], v27, s[2:3] offset:16
	s_waitcnt vmcnt(30)
	v_fmac_f32_dpp v8, v240, v88 row_newbcast:7 row_mask:0xf bank_mask:0xf
	v_fmac_f32_dpp v9, v240, v89 row_newbcast:7 row_mask:0xf bank_mask:0xf
	v_fmac_f32_dpp v10, v240, v90 row_newbcast:7 row_mask:0xf bank_mask:0xf
	v_fmac_f32_dpp v11, v240, v91 row_newbcast:7 row_mask:0xf bank_mask:0xf
	v_fmac_f32_dpp v12, v240, v92 row_newbcast:7 row_mask:0xf bank_mask:0xf
	v_fmac_f32_dpp v13, v240, v93 row_newbcast:7 row_mask:0xf bank_mask:0xf
	v_fmac_f32_dpp v14, v240, v94 row_newbcast:7 row_mask:0xf bank_mask:0xf
	v_fmac_f32_dpp v15, v240, v95 row_newbcast:7 row_mask:0xf bank_mask:0xf
	global_load_dwordx4 v[88:91], v27, s[2:3] offset:2048
	global_load_dwordx4 v[92:95], v27, s[2:3] offset:2064
	s_waitcnt vmcnt(30)
	v_fmac_f32_dpp v8, v240, v96 row_newbcast:8 row_mask:0xf bank_mask:0xf
	v_fmac_f32_dpp v9, v240, v97 row_newbcast:8 row_mask:0xf bank_mask:0xf
	v_fmac_f32_dpp v10, v240, v98 row_newbcast:8 row_mask:0xf bank_mask:0xf
	v_fmac_f32_dpp v11, v240, v99 row_newbcast:8 row_mask:0xf bank_mask:0xf
	v_fmac_f32_dpp v12, v240, v100 row_newbcast:8 row_mask:0xf bank_mask:0xf
	v_fmac_f32_dpp v13, v240, v101 row_newbcast:8 row_mask:0xf bank_mask:0xf
	v_fmac_f32_dpp v14, v240, v102 row_newbcast:8 row_mask:0xf bank_mask:0xf
	v_fmac_f32_dpp v15, v240, v103 row_newbcast:8 row_mask:0xf bank_mask:0xf
	global_load_dwordx4 v[96:99], v28, s[2:3]
	global_load_dwordx4 v[100:103], v28, s[2:3] offset:16
	s_waitcnt vmcnt(30)
	v_fmac_f32_dpp v8, v240, v104 row_newbcast:9 row_mask:0xf bank_mask:0xf
	v_fmac_f32_dpp v9, v240, v105 row_newbcast:9 row_mask:0xf bank_mask:0xf
	v_fmac_f32_dpp v10, v240, v106 row_newbcast:9 row_mask:0xf bank_mask:0xf
	v_fmac_f32_dpp v11, v240, v107 row_newbcast:9 row_mask:0xf bank_mask:0xf
	v_fmac_f32_dpp v12, v240, v108 row_newbcast:9 row_mask:0xf bank_mask:0xf
	v_fmac_f32_dpp v13, v240, v109 row_newbcast:9 row_mask:0xf bank_mask:0xf
	v_fmac_f32_dpp v14, v240, v110 row_newbcast:9 row_mask:0xf bank_mask:0xf
	v_fmac_f32_dpp v15, v240, v111 row_newbcast:9 row_mask:0xf bank_mask:0xf
	global_load_dwordx4 v[104:107], v28, s[2:3] offset:2048
	global_load_dwordx4 v[108:111], v28, s[2:3] offset:2064
	s_waitcnt vmcnt(30)
	v_fmac_f32_dpp v8, v240, v112 row_newbcast:10 row_mask:0xf bank_mask:0xf
	v_fmac_f32_dpp v9, v240, v113 row_newbcast:10 row_mask:0xf bank_mask:0xf
	v_fmac_f32_dpp v10, v240, v114 row_newbcast:10 row_mask:0xf bank_mask:0xf
	v_fmac_f32_dpp v11, v240, v115 row_newbcast:10 row_mask:0xf bank_mask:0xf
	v_fmac_f32_dpp v12, v240, v116 row_newbcast:10 row_mask:0xf bank_mask:0xf
	v_fmac_f32_dpp v13, v240, v117 row_newbcast:10 row_mask:0xf bank_mask:0xf
	v_fmac_f32_dpp v14, v240, v118 row_newbcast:10 row_mask:0xf bank_mask:0xf
	v_fmac_f32_dpp v15, v240, v119 row_newbcast:10 row_mask:0xf bank_mask:0xf
	global_load_dwordx4 v[112:115], v29, s[2:3]
	global_load_dwordx4 v[116:119], v29, s[2:3] offset:16
	s_waitcnt vmcnt(30)
	v_fmac_f32_dpp v8, v240, v120 row_newbcast:11 row_mask:0xf bank_mask:0xf
	v_fmac_f32_dpp v9, v240, v121 row_newbcast:11 row_mask:0xf bank_mask:0xf
	v_fmac_f32_dpp v10, v240, v122 row_newbcast:11 row_mask:0xf bank_mask:0xf
	v_fmac_f32_dpp v11, v240, v123 row_newbcast:11 row_mask:0xf bank_mask:0xf
	v_fmac_f32_dpp v12, v240, v124 row_newbcast:11 row_mask:0xf bank_mask:0xf
	v_fmac_f32_dpp v13, v240, v125 row_newbcast:11 row_mask:0xf bank_mask:0xf
	v_fmac_f32_dpp v14, v240, v126 row_newbcast:11 row_mask:0xf bank_mask:0xf
	v_fmac_f32_dpp v15, v240, v127 row_newbcast:11 row_mask:0xf bank_mask:0xf
	global_load_dwordx4 v[120:123], v29, s[2:3] offset:2048
	global_load_dwordx4 v[124:127], v29, s[2:3] offset:2064
	s_waitcnt vmcnt(30)
	v_fmac_f32_dpp v8, v240, v128 row_newbcast:12 row_mask:0xf bank_mask:0xf
	v_fmac_f32_dpp v9, v240, v129 row_newbcast:12 row_mask:0xf bank_mask:0xf
	v_fmac_f32_dpp v10, v240, v130 row_newbcast:12 row_mask:0xf bank_mask:0xf
	v_fmac_f32_dpp v11, v240, v131 row_newbcast:12 row_mask:0xf bank_mask:0xf
	v_fmac_f32_dpp v12, v240, v132 row_newbcast:12 row_mask:0xf bank_mask:0xf
	v_fmac_f32_dpp v13, v240, v133 row_newbcast:12 row_mask:0xf bank_mask:0xf
	v_fmac_f32_dpp v14, v240, v134 row_newbcast:12 row_mask:0xf bank_mask:0xf
	v_fmac_f32_dpp v15, v240, v135 row_newbcast:12 row_mask:0xf bank_mask:0xf
	global_load_dwordx4 v[128:131], v30, s[2:3]
	global_load_dwordx4 v[132:135], v30, s[2:3] offset:16
	s_waitcnt vmcnt(30)
	v_fmac_f32_dpp v8, v240, v136 row_newbcast:13 row_mask:0xf bank_mask:0xf
	v_fmac_f32_dpp v9, v240, v137 row_newbcast:13 row_mask:0xf bank_mask:0xf
	v_fmac_f32_dpp v10, v240, v138 row_newbcast:13 row_mask:0xf bank_mask:0xf
	v_fmac_f32_dpp v11, v240, v139 row_newbcast:13 row_mask:0xf bank_mask:0xf
	v_fmac_f32_dpp v12, v240, v140 row_newbcast:13 row_mask:0xf bank_mask:0xf
	v_fmac_f32_dpp v13, v240, v141 row_newbcast:13 row_mask:0xf bank_mask:0xf
	v_fmac_f32_dpp v14, v240, v142 row_newbcast:13 row_mask:0xf bank_mask:0xf
	v_fmac_f32_dpp v15, v240, v143 row_newbcast:13 row_mask:0xf bank_mask:0xf
	global_load_dwordx4 v[136:139], v30, s[2:3] offset:2048
	global_load_dwordx4 v[140:143], v30, s[2:3] offset:2064
	s_waitcnt vmcnt(30)
	v_fmac_f32_dpp v8, v240, v144 row_newbcast:14 row_mask:0xf bank_mask:0xf
	v_fmac_f32_dpp v9, v240, v145 row_newbcast:14 row_mask:0xf bank_mask:0xf
	v_fmac_f32_dpp v10, v240, v146 row_newbcast:14 row_mask:0xf bank_mask:0xf
	v_fmac_f32_dpp v11, v240, v147 row_newbcast:14 row_mask:0xf bank_mask:0xf
	v_fmac_f32_dpp v12, v240, v148 row_newbcast:14 row_mask:0xf bank_mask:0xf
	v_fmac_f32_dpp v13, v240, v149 row_newbcast:14 row_mask:0xf bank_mask:0xf
	v_fmac_f32_dpp v14, v240, v150 row_newbcast:14 row_mask:0xf bank_mask:0xf
	v_fmac_f32_dpp v15, v240, v151 row_newbcast:14 row_mask:0xf bank_mask:0xf
	global_load_dwordx4 v[144:147], v31, s[2:3]
	global_load_dwordx4 v[148:151], v31, s[2:3] offset:16
	s_waitcnt vmcnt(30)
	v_fmac_f32_dpp v8, v240, v152 row_newbcast:15 row_mask:0xf bank_mask:0xf
	v_fmac_f32_dpp v9, v240, v153 row_newbcast:15 row_mask:0xf bank_mask:0xf
	v_fmac_f32_dpp v10, v240, v154 row_newbcast:15 row_mask:0xf bank_mask:0xf
	v_fmac_f32_dpp v11, v240, v155 row_newbcast:15 row_mask:0xf bank_mask:0xf
	v_fmac_f32_dpp v12, v240, v156 row_newbcast:15 row_mask:0xf bank_mask:0xf
	v_fmac_f32_dpp v13, v240, v157 row_newbcast:15 row_mask:0xf bank_mask:0xf
	v_fmac_f32_dpp v14, v240, v158 row_newbcast:15 row_mask:0xf bank_mask:0xf
	v_fmac_f32_dpp v15, v240, v159 row_newbcast:15 row_mask:0xf bank_mask:0xf
	global_load_dwordx4 v[152:155], v31, s[2:3] offset:2048
	global_load_dwordx4 v[156:159], v31, s[2:3] offset:2064
	s_waitcnt vmcnt(30)
	v_mul_f32_e32 v160, v32, v0
	v_fmac_f32_e32 v160, v33, v1
	v_fmac_f32_e32 v160, v34, v2
	v_fmac_f32_e32 v160, v35, v3
	v_fmac_f32_e32 v160, v36, v4
	v_fmac_f32_e32 v160, v37, v5
	v_fmac_f32_e32 v160, v38, v6
	v_fmac_f32_e32 v160, v39, v7
	global_load_dwordx4 v[32:35], v24, s[4:5]
	global_load_dwordx4 v[36:39], v24, s[4:5] offset:16
	s_waitcnt vmcnt(30)
	v_mul_f32_e32 v161, v40, v0
	v_fmac_f32_e32 v161, v41, v1
	v_fmac_f32_e32 v161, v42, v2
	v_fmac_f32_e32 v161, v43, v3
	v_fmac_f32_e32 v161, v44, v4
	v_fmac_f32_e32 v161, v45, v5
	v_fmac_f32_e32 v161, v46, v6
	v_fmac_f32_e32 v161, v47, v7
	global_load_dwordx4 v[40:43], v24, s[4:5] offset:2048
	global_load_dwordx4 v[44:47], v24, s[4:5] offset:2064
	s_waitcnt vmcnt(30)
	v_mul_f32_e32 v162, v48, v0
	v_fmac_f32_e32 v162, v49, v1
	v_fmac_f32_e32 v162, v50, v2
	v_fmac_f32_e32 v162, v51, v3
	v_fmac_f32_e32 v162, v52, v4
	v_fmac_f32_e32 v162, v53, v5
	v_fmac_f32_e32 v162, v54, v6
	v_fmac_f32_e32 v162, v55, v7
	global_load_dwordx4 v[48:51], v25, s[4:5]
	global_load_dwordx4 v[52:55], v25, s[4:5] offset:16
	s_waitcnt vmcnt(30)
	v_mul_f32_e32 v163, v56, v0
	v_fmac_f32_e32 v163, v57, v1
	v_fmac_f32_e32 v163, v58, v2
	v_fmac_f32_e32 v163, v59, v3
	v_fmac_f32_e32 v163, v60, v4
	v_fmac_f32_e32 v163, v61, v5
	v_fmac_f32_e32 v163, v62, v6
	v_fmac_f32_e32 v163, v63, v7
	global_load_dwordx4 v[56:59], v25, s[4:5] offset:2048
	global_load_dwordx4 v[60:63], v25, s[4:5] offset:2064
	s_waitcnt vmcnt(30)
	v_mul_f32_e32 v164, v64, v0
	v_fmac_f32_e32 v164, v65, v1
	v_fmac_f32_e32 v164, v66, v2
	v_fmac_f32_e32 v164, v67, v3
	v_fmac_f32_e32 v164, v68, v4
	v_fmac_f32_e32 v164, v69, v5
	v_fmac_f32_e32 v164, v70, v6
	v_fmac_f32_e32 v164, v71, v7
	global_load_dwordx4 v[64:67], v26, s[4:5]
	global_load_dwordx4 v[68:71], v26, s[4:5] offset:16
	s_waitcnt vmcnt(30)
	v_mul_f32_e32 v165, v72, v0
	v_fmac_f32_e32 v165, v73, v1
	v_fmac_f32_e32 v165, v74, v2
	v_fmac_f32_e32 v165, v75, v3
	v_fmac_f32_e32 v165, v76, v4
	v_fmac_f32_e32 v165, v77, v5
	v_fmac_f32_e32 v165, v78, v6
	v_fmac_f32_e32 v165, v79, v7
	global_load_dwordx4 v[72:75], v26, s[4:5] offset:2048
	global_load_dwordx4 v[76:79], v26, s[4:5] offset:2064
	s_waitcnt vmcnt(30)
	v_mul_f32_e32 v166, v80, v0
	v_fmac_f32_e32 v166, v81, v1
	v_fmac_f32_e32 v166, v82, v2
	v_fmac_f32_e32 v166, v83, v3
	v_fmac_f32_e32 v166, v84, v4
	v_fmac_f32_e32 v166, v85, v5
	v_fmac_f32_e32 v166, v86, v6
	v_fmac_f32_e32 v166, v87, v7
	global_load_dwordx4 v[80:83], v27, s[4:5]
	global_load_dwordx4 v[84:87], v27, s[4:5] offset:16
	s_waitcnt vmcnt(30)
	v_mul_f32_e32 v167, v88, v0
	v_fmac_f32_e32 v167, v89, v1
	v_fmac_f32_e32 v167, v90, v2
	v_fmac_f32_e32 v167, v91, v3
	v_fmac_f32_e32 v167, v92, v4
	v_fmac_f32_e32 v167, v93, v5
	v_fmac_f32_e32 v167, v94, v6
	v_fmac_f32_e32 v167, v95, v7
	global_load_dwordx4 v[88:91], v27, s[4:5] offset:2048
	global_load_dwordx4 v[92:95], v27, s[4:5] offset:2064
	s_waitcnt vmcnt(30)
	v_mul_f32_e32 v168, v96, v0
	v_fmac_f32_e32 v168, v97, v1
	v_fmac_f32_e32 v168, v98, v2
	v_fmac_f32_e32 v168, v99, v3
	v_fmac_f32_e32 v168, v100, v4
	v_fmac_f32_e32 v168, v101, v5
	v_fmac_f32_e32 v168, v102, v6
	v_fmac_f32_e32 v168, v103, v7
	global_load_dwordx4 v[96:99], v28, s[4:5]
	global_load_dwordx4 v[100:103], v28, s[4:5] offset:16
	s_waitcnt vmcnt(30)
	v_mul_f32_e32 v169, v104, v0
	v_fmac_f32_e32 v169, v105, v1
	v_fmac_f32_e32 v169, v106, v2
	v_fmac_f32_e32 v169, v107, v3
	v_fmac_f32_e32 v169, v108, v4
	v_fmac_f32_e32 v169, v109, v5
	v_fmac_f32_e32 v169, v110, v6
	v_fmac_f32_e32 v169, v111, v7
	global_load_dwordx4 v[104:107], v28, s[4:5] offset:2048
	global_load_dwordx4 v[108:111], v28, s[4:5] offset:2064
	s_waitcnt vmcnt(30)
	v_mul_f32_e32 v170, v112, v0
	v_fmac_f32_e32 v170, v113, v1
	v_fmac_f32_e32 v170, v114, v2
	v_fmac_f32_e32 v170, v115, v3
	v_fmac_f32_e32 v170, v116, v4
	v_fmac_f32_e32 v170, v117, v5
	v_fmac_f32_e32 v170, v118, v6
	v_fmac_f32_e32 v170, v119, v7
	global_load_dwordx4 v[112:115], v29, s[4:5]
	global_load_dwordx4 v[116:119], v29, s[4:5] offset:16
	s_waitcnt vmcnt(30)
	v_mul_f32_e32 v171, v120, v0
	v_fmac_f32_e32 v171, v121, v1
	v_fmac_f32_e32 v171, v122, v2
	v_fmac_f32_e32 v171, v123, v3
	v_fmac_f32_e32 v171, v124, v4
	v_fmac_f32_e32 v171, v125, v5
	v_fmac_f32_e32 v171, v126, v6
	v_fmac_f32_e32 v171, v127, v7
	global_load_dwordx4 v[120:123], v29, s[4:5] offset:2048
	global_load_dwordx4 v[124:127], v29, s[4:5] offset:2064
	s_waitcnt vmcnt(30)
	v_mul_f32_e32 v172, v128, v0
	v_fmac_f32_e32 v172, v129, v1
	v_fmac_f32_e32 v172, v130, v2
	v_fmac_f32_e32 v172, v131, v3
	v_fmac_f32_e32 v172, v132, v4
	v_fmac_f32_e32 v172, v133, v5
	v_fmac_f32_e32 v172, v134, v6
	v_fmac_f32_e32 v172, v135, v7
	global_load_dwordx4 v[128:131], v30, s[4:5]
	global_load_dwordx4 v[132:135], v30, s[4:5] offset:16
	s_waitcnt vmcnt(30)
	v_mul_f32_e32 v173, v136, v0
	v_fmac_f32_e32 v173, v137, v1
	v_fmac_f32_e32 v173, v138, v2
	v_fmac_f32_e32 v173, v139, v3
	v_fmac_f32_e32 v173, v140, v4
	v_fmac_f32_e32 v173, v141, v5
	v_fmac_f32_e32 v173, v142, v6
	v_fmac_f32_e32 v173, v143, v7
	global_load_dwordx4 v[136:139], v30, s[4:5] offset:2048
	global_load_dwordx4 v[140:143], v30, s[4:5] offset:2064
	s_waitcnt vmcnt(30)
	v_mul_f32_e32 v174, v144, v0
	v_fmac_f32_e32 v174, v145, v1
	v_fmac_f32_e32 v174, v146, v2
	v_fmac_f32_e32 v174, v147, v3
	v_fmac_f32_e32 v174, v148, v4
	v_fmac_f32_e32 v174, v149, v5
	v_fmac_f32_e32 v174, v150, v6
	v_fmac_f32_e32 v174, v151, v7
	global_load_dwordx4 v[144:147], v31, s[4:5]
	global_load_dwordx4 v[148:151], v31, s[4:5] offset:16
	s_waitcnt vmcnt(30)
	v_mul_f32_e32 v175, v152, v0
	v_fmac_f32_e32 v175, v153, v1
	v_fmac_f32_e32 v175, v154, v2
	v_fmac_f32_e32 v175, v155, v3
	v_fmac_f32_e32 v175, v156, v4
	v_fmac_f32_e32 v175, v157, v5
	v_fmac_f32_e32 v175, v158, v6
	v_fmac_f32_e32 v175, v159, v7
	global_load_dwordx4 v[152:155], v31, s[4:5] offset:2048
	global_load_dwordx4 v[156:159], v31, s[4:5] offset:2064
	v_add_f32_dpp v160, v160, v160 row_ror:8 row_mask:0xf bank_mask:0x3
	v_add_f32_dpp v160, v168, v168 row_ror:8 row_mask:0xf bank_mask:0xc
	v_add_f32_dpp v161, v161, v161 row_ror:8 row_mask:0xf bank_mask:0x3
	v_add_f32_dpp v161, v169, v169 row_ror:8 row_mask:0xf bank_mask:0xc
	v_add_f32_dpp v162, v162, v162 row_ror:8 row_mask:0xf bank_mask:0x3
	v_add_f32_dpp v162, v170, v170 row_ror:8 row_mask:0xf bank_mask:0xc
	v_add_f32_dpp v163, v163, v163 row_ror:8 row_mask:0xf bank_mask:0x3
	v_add_f32_dpp v163, v171, v171 row_ror:8 row_mask:0xf bank_mask:0xc
	v_add_f32_dpp v164, v164, v164 row_ror:8 row_mask:0xf bank_mask:0x3
	v_add_f32_dpp v164, v172, v172 row_ror:8 row_mask:0xf bank_mask:0xc
	v_add_f32_dpp v165, v165, v165 row_ror:8 row_mask:0xf bank_mask:0x3
	v_add_f32_dpp v165, v173, v173 row_ror:8 row_mask:0xf bank_mask:0xc
	v_add_f32_dpp v166, v166, v166 row_ror:8 row_mask:0xf bank_mask:0x3
	v_add_f32_dpp v166, v174, v174 row_ror:8 row_mask:0xf bank_mask:0xc
	v_add_f32_dpp v167, v167, v167 row_ror:8 row_mask:0xf bank_mask:0x3
	v_add_f32_dpp v167, v175, v175 row_ror:8 row_mask:0xf bank_mask:0xc
	v_add_f32_dpp v160, v160, v160 row_shl:4 row_mask:0xf bank_mask:0x5
	v_add_f32_dpp v160, v164, v164 row_shr:4 row_mask:0xf bank_mask:0xa
	v_add_f32_dpp v161, v161, v161 row_shl:4 row_mask:0xf bank_mask:0x5
	v_add_f32_dpp v161, v165, v165 row_shr:4 row_mask:0xf bank_mask:0xa
	v_add_f32_dpp v162, v162, v162 row_shl:4 row_mask:0xf bank_mask:0x5
	v_add_f32_dpp v162, v166, v166 row_shr:4 row_mask:0xf bank_mask:0xa
	v_add_f32_dpp v163, v163, v163 row_shl:4 row_mask:0xf bank_mask:0x5
	v_add_f32_dpp v163, v167, v167 row_shr:4 row_mask:0xf bank_mask:0xa
	v_and_b32_e32 v176, 2, v18
	v_cmp_ne_u32_e32 vcc, 0, v176
	v_add_f32_dpp v230, v160, v160 quad_perm:[2,3,0,1] row_mask:0xf bank_mask:0xf
	v_add_f32_dpp v231, v162, v162 quad_perm:[2,3,0,1] row_mask:0xf bank_mask:0xf
	v_add_f32_dpp v232, v161, v161 quad_perm:[2,3,0,1] row_mask:0xf bank_mask:0xf
	v_add_f32_dpp v233, v163, v163 quad_perm:[2,3,0,1] row_mask:0xf bank_mask:0xf
	v_cndmask_b32_e32 v230, v230, v231, vcc
	v_cndmask_b32_e32 v232, v232, v233, vcc
	v_and_b32_e32 v176, 1, v18
	v_cmp_ne_u32_e32 vcc, 0, v176
	v_add_f32_dpp v231, v230, v230 quad_perm:[1,0,3,2] row_mask:0xf bank_mask:0xf
	v_add_f32_dpp v233, v232, v232 quad_perm:[1,0,3,2] row_mask:0xf bank_mask:0xf
	s_nop 1
	v_cndmask_b32_e32 v241, v231, v233, vcc
	s_nop 1
	v_max_f32_dpp v242, v241, v241 row_ror:8 row_mask:0xf bank_mask:0xf
	s_nop 1
	v_max_f32_dpp v242, v242, v242 row_ror:4 row_mask:0xf bank_mask:0xf
	s_nop 1
	v_max_f32_dpp v242, v242, v242 row_ror:2 row_mask:0xf bank_mask:0xf
	s_nop 1
	v_max_f32_dpp v242, v242, v242 row_ror:1 row_mask:0xf bank_mask:0xf
	ds_bpermute_b32 v234, v238, v242
	s_waitcnt lgkmcnt(0)
	v_max_f32_e32 v242, v242, v234
	ds_bpermute_b32 v234, v239, v242
	s_waitcnt lgkmcnt(0)
	v_max_f32_e32 v242, v242, v234
	v_max_f32_e32 v242, v16, v242
	v_sub_f32_e32 v243, v16, v242
	v_sub_f32_e32 v240, v241, v242
	v_mul_f32_e32 v243, 0x3fb8aa3b, v243
	v_mul_f32_e32 v240, 0x3fb8aa3b, v240
	v_exp_f32_e32 v243, v243
	v_exp_f32_e32 v240, v240
	v_mov_b32_e32 v16, v242
	s_nop 0
	s_nop 1
	v_add_f32_dpp v235, v240, v240 row_ror:8 row_mask:0xf bank_mask:0xf
	s_nop 1
	v_add_f32_dpp v235, v235, v235 row_ror:4 row_mask:0xf bank_mask:0xf
	s_nop 1
	v_add_f32_dpp v235, v235, v235 row_ror:2 row_mask:0xf bank_mask:0xf
	s_nop 1
	v_add_f32_dpp v235, v235, v235 row_ror:1 row_mask:0xf bank_mask:0xf
	ds_bpermute_b32 v234, v238, v235
	s_waitcnt lgkmcnt(0)
	v_add_f32_e32 v235, v235, v234
	ds_bpermute_b32 v234, v239, v235
	s_waitcnt lgkmcnt(0)
	v_add_f32_e32 v235, v235, v234
	v_fma_f32 v17, v17, v243, v235
	v_mul_f32_e32 v8, v8, v243
	v_mul_f32_e32 v9, v9, v243
	v_mul_f32_e32 v10, v10, v243
	v_mul_f32_e32 v11, v11, v243
	v_mul_f32_e32 v12, v12, v243
	v_mul_f32_e32 v13, v13, v243
	v_mul_f32_e32 v14, v14, v243
	v_mul_f32_e32 v15, v15, v243
	s_waitcnt vmcnt(30)
	v_fmac_f32_dpp v8, v240, v32 row_newbcast:0 row_mask:0xf bank_mask:0xf
	v_fmac_f32_dpp v9, v240, v33 row_newbcast:0 row_mask:0xf bank_mask:0xf
	v_fmac_f32_dpp v10, v240, v34 row_newbcast:0 row_mask:0xf bank_mask:0xf
	v_fmac_f32_dpp v11, v240, v35 row_newbcast:0 row_mask:0xf bank_mask:0xf
	v_fmac_f32_dpp v12, v240, v36 row_newbcast:0 row_mask:0xf bank_mask:0xf
	v_fmac_f32_dpp v13, v240, v37 row_newbcast:0 row_mask:0xf bank_mask:0xf
	v_fmac_f32_dpp v14, v240, v38 row_newbcast:0 row_mask:0xf bank_mask:0xf
	v_fmac_f32_dpp v15, v240, v39 row_newbcast:0 row_mask:0xf bank_mask:0xf
	s_waitcnt vmcnt(28)
	v_fmac_f32_dpp v8, v240, v40 row_newbcast:1 row_mask:0xf bank_mask:0xf
	v_fmac_f32_dpp v9, v240, v41 row_newbcast:1 row_mask:0xf bank_mask:0xf
	v_fmac_f32_dpp v10, v240, v42 row_newbcast:1 row_mask:0xf bank_mask:0xf
	v_fmac_f32_dpp v11, v240, v43 row_newbcast:1 row_mask:0xf bank_mask:0xf
	v_fmac_f32_dpp v12, v240, v44 row_newbcast:1 row_mask:0xf bank_mask:0xf
	v_fmac_f32_dpp v13, v240, v45 row_newbcast:1 row_mask:0xf bank_mask:0xf
	v_fmac_f32_dpp v14, v240, v46 row_newbcast:1 row_mask:0xf bank_mask:0xf
	v_fmac_f32_dpp v15, v240, v47 row_newbcast:1 row_mask:0xf bank_mask:0xf
	s_waitcnt vmcnt(26)
	v_fmac_f32_dpp v8, v240, v48 row_newbcast:2 row_mask:0xf bank_mask:0xf
	v_fmac_f32_dpp v9, v240, v49 row_newbcast:2 row_mask:0xf bank_mask:0xf
	v_fmac_f32_dpp v10, v240, v50 row_newbcast:2 row_mask:0xf bank_mask:0xf
	v_fmac_f32_dpp v11, v240, v51 row_newbcast:2 row_mask:0xf bank_mask:0xf
	v_fmac_f32_dpp v12, v240, v52 row_newbcast:2 row_mask:0xf bank_mask:0xf
	v_fmac_f32_dpp v13, v240, v53 row_newbcast:2 row_mask:0xf bank_mask:0xf
	v_fmac_f32_dpp v14, v240, v54 row_newbcast:2 row_mask:0xf bank_mask:0xf
	v_fmac_f32_dpp v15, v240, v55 row_newbcast:2 row_mask:0xf bank_mask:0xf
	s_waitcnt vmcnt(24)
	v_fmac_f32_dpp v8, v240, v56 row_newbcast:3 row_mask:0xf bank_mask:0xf
	v_fmac_f32_dpp v9, v240, v57 row_newbcast:3 row_mask:0xf bank_mask:0xf
	v_fmac_f32_dpp v10, v240, v58 row_newbcast:3 row_mask:0xf bank_mask:0xf
	v_fmac_f32_dpp v11, v240, v59 row_newbcast:3 row_mask:0xf bank_mask:0xf
	v_fmac_f32_dpp v12, v240, v60 row_newbcast:3 row_mask:0xf bank_mask:0xf
	v_fmac_f32_dpp v13, v240, v61 row_newbcast:3 row_mask:0xf bank_mask:0xf
	v_fmac_f32_dpp v14, v240, v62 row_newbcast:3 row_mask:0xf bank_mask:0xf
	v_fmac_f32_dpp v15, v240, v63 row_newbcast:3 row_mask:0xf bank_mask:0xf
	s_waitcnt vmcnt(22)
	v_fmac_f32_dpp v8, v240, v64 row_newbcast:4 row_mask:0xf bank_mask:0xf
	v_fmac_f32_dpp v9, v240, v65 row_newbcast:4 row_mask:0xf bank_mask:0xf
	v_fmac_f32_dpp v10, v240, v66 row_newbcast:4 row_mask:0xf bank_mask:0xf
	v_fmac_f32_dpp v11, v240, v67 row_newbcast:4 row_mask:0xf bank_mask:0xf
	v_fmac_f32_dpp v12, v240, v68 row_newbcast:4 row_mask:0xf bank_mask:0xf
	v_fmac_f32_dpp v13, v240, v69 row_newbcast:4 row_mask:0xf bank_mask:0xf
	v_fmac_f32_dpp v14, v240, v70 row_newbcast:4 row_mask:0xf bank_mask:0xf
	v_fmac_f32_dpp v15, v240, v71 row_newbcast:4 row_mask:0xf bank_mask:0xf
	s_waitcnt vmcnt(20)
	v_fmac_f32_dpp v8, v240, v72 row_newbcast:5 row_mask:0xf bank_mask:0xf
	v_fmac_f32_dpp v9, v240, v73 row_newbcast:5 row_mask:0xf bank_mask:0xf
	v_fmac_f32_dpp v10, v240, v74 row_newbcast:5 row_mask:0xf bank_mask:0xf
	v_fmac_f32_dpp v11, v240, v75 row_newbcast:5 row_mask:0xf bank_mask:0xf
	v_fmac_f32_dpp v12, v240, v76 row_newbcast:5 row_mask:0xf bank_mask:0xf
	v_fmac_f32_dpp v13, v240, v77 row_newbcast:5 row_mask:0xf bank_mask:0xf
	v_fmac_f32_dpp v14, v240, v78 row_newbcast:5 row_mask:0xf bank_mask:0xf
	v_fmac_f32_dpp v15, v240, v79 row_newbcast:5 row_mask:0xf bank_mask:0xf
	s_waitcnt vmcnt(18)
	v_fmac_f32_dpp v8, v240, v80 row_newbcast:6 row_mask:0xf bank_mask:0xf
	v_fmac_f32_dpp v9, v240, v81 row_newbcast:6 row_mask:0xf bank_mask:0xf
	v_fmac_f32_dpp v10, v240, v82 row_newbcast:6 row_mask:0xf bank_mask:0xf
	v_fmac_f32_dpp v11, v240, v83 row_newbcast:6 row_mask:0xf bank_mask:0xf
	v_fmac_f32_dpp v12, v240, v84 row_newbcast:6 row_mask:0xf bank_mask:0xf
	v_fmac_f32_dpp v13, v240, v85 row_newbcast:6 row_mask:0xf bank_mask:0xf
	v_fmac_f32_dpp v14, v240, v86 row_newbcast:6 row_mask:0xf bank_mask:0xf
	v_fmac_f32_dpp v15, v240, v87 row_newbcast:6 row_mask:0xf bank_mask:0xf
	s_waitcnt vmcnt(16)
	v_fmac_f32_dpp v8, v240, v88 row_newbcast:7 row_mask:0xf bank_mask:0xf
	v_fmac_f32_dpp v9, v240, v89 row_newbcast:7 row_mask:0xf bank_mask:0xf
	v_fmac_f32_dpp v10, v240, v90 row_newbcast:7 row_mask:0xf bank_mask:0xf
	v_fmac_f32_dpp v11, v240, v91 row_newbcast:7 row_mask:0xf bank_mask:0xf
	v_fmac_f32_dpp v12, v240, v92 row_newbcast:7 row_mask:0xf bank_mask:0xf
	v_fmac_f32_dpp v13, v240, v93 row_newbcast:7 row_mask:0xf bank_mask:0xf
	v_fmac_f32_dpp v14, v240, v94 row_newbcast:7 row_mask:0xf bank_mask:0xf
	v_fmac_f32_dpp v15, v240, v95 row_newbcast:7 row_mask:0xf bank_mask:0xf
	s_waitcnt vmcnt(14)
	v_fmac_f32_dpp v8, v240, v96 row_newbcast:8 row_mask:0xf bank_mask:0xf
	v_fmac_f32_dpp v9, v240, v97 row_newbcast:8 row_mask:0xf bank_mask:0xf
	v_fmac_f32_dpp v10, v240, v98 row_newbcast:8 row_mask:0xf bank_mask:0xf
	v_fmac_f32_dpp v11, v240, v99 row_newbcast:8 row_mask:0xf bank_mask:0xf
	v_fmac_f32_dpp v12, v240, v100 row_newbcast:8 row_mask:0xf bank_mask:0xf
	v_fmac_f32_dpp v13, v240, v101 row_newbcast:8 row_mask:0xf bank_mask:0xf
	v_fmac_f32_dpp v14, v240, v102 row_newbcast:8 row_mask:0xf bank_mask:0xf
	v_fmac_f32_dpp v15, v240, v103 row_newbcast:8 row_mask:0xf bank_mask:0xf
	s_waitcnt vmcnt(12)
	v_fmac_f32_dpp v8, v240, v104 row_newbcast:9 row_mask:0xf bank_mask:0xf
	v_fmac_f32_dpp v9, v240, v105 row_newbcast:9 row_mask:0xf bank_mask:0xf
	v_fmac_f32_dpp v10, v240, v106 row_newbcast:9 row_mask:0xf bank_mask:0xf
	v_fmac_f32_dpp v11, v240, v107 row_newbcast:9 row_mask:0xf bank_mask:0xf
	v_fmac_f32_dpp v12, v240, v108 row_newbcast:9 row_mask:0xf bank_mask:0xf
	v_fmac_f32_dpp v13, v240, v109 row_newbcast:9 row_mask:0xf bank_mask:0xf
	v_fmac_f32_dpp v14, v240, v110 row_newbcast:9 row_mask:0xf bank_mask:0xf
	v_fmac_f32_dpp v15, v240, v111 row_newbcast:9 row_mask:0xf bank_mask:0xf
	s_waitcnt vmcnt(10)
	v_fmac_f32_dpp v8, v240, v112 row_newbcast:10 row_mask:0xf bank_mask:0xf
	v_fmac_f32_dpp v9, v240, v113 row_newbcast:10 row_mask:0xf bank_mask:0xf
	v_fmac_f32_dpp v10, v240, v114 row_newbcast:10 row_mask:0xf bank_mask:0xf
	v_fmac_f32_dpp v11, v240, v115 row_newbcast:10 row_mask:0xf bank_mask:0xf
	v_fmac_f32_dpp v12, v240, v116 row_newbcast:10 row_mask:0xf bank_mask:0xf
	v_fmac_f32_dpp v13, v240, v117 row_newbcast:10 row_mask:0xf bank_mask:0xf
	v_fmac_f32_dpp v14, v240, v118 row_newbcast:10 row_mask:0xf bank_mask:0xf
	v_fmac_f32_dpp v15, v240, v119 row_newbcast:10 row_mask:0xf bank_mask:0xf
	s_waitcnt vmcnt(8)
	v_fmac_f32_dpp v8, v240, v120 row_newbcast:11 row_mask:0xf bank_mask:0xf
	v_fmac_f32_dpp v9, v240, v121 row_newbcast:11 row_mask:0xf bank_mask:0xf
	v_fmac_f32_dpp v10, v240, v122 row_newbcast:11 row_mask:0xf bank_mask:0xf
	v_fmac_f32_dpp v11, v240, v123 row_newbcast:11 row_mask:0xf bank_mask:0xf
	v_fmac_f32_dpp v12, v240, v124 row_newbcast:11 row_mask:0xf bank_mask:0xf
	v_fmac_f32_dpp v13, v240, v125 row_newbcast:11 row_mask:0xf bank_mask:0xf
	v_fmac_f32_dpp v14, v240, v126 row_newbcast:11 row_mask:0xf bank_mask:0xf
	v_fmac_f32_dpp v15, v240, v127 row_newbcast:11 row_mask:0xf bank_mask:0xf
	s_waitcnt vmcnt(6)
	v_fmac_f32_dpp v8, v240, v128 row_newbcast:12 row_mask:0xf bank_mask:0xf
	v_fmac_f32_dpp v9, v240, v129 row_newbcast:12 row_mask:0xf bank_mask:0xf
	v_fmac_f32_dpp v10, v240, v130 row_newbcast:12 row_mask:0xf bank_mask:0xf
	v_fmac_f32_dpp v11, v240, v131 row_newbcast:12 row_mask:0xf bank_mask:0xf
	v_fmac_f32_dpp v12, v240, v132 row_newbcast:12 row_mask:0xf bank_mask:0xf
	v_fmac_f32_dpp v13, v240, v133 row_newbcast:12 row_mask:0xf bank_mask:0xf
	v_fmac_f32_dpp v14, v240, v134 row_newbcast:12 row_mask:0xf bank_mask:0xf
	v_fmac_f32_dpp v15, v240, v135 row_newbcast:12 row_mask:0xf bank_mask:0xf
	s_waitcnt vmcnt(4)
	v_fmac_f32_dpp v8, v240, v136 row_newbcast:13 row_mask:0xf bank_mask:0xf
	v_fmac_f32_dpp v9, v240, v137 row_newbcast:13 row_mask:0xf bank_mask:0xf
	v_fmac_f32_dpp v10, v240, v138 row_newbcast:13 row_mask:0xf bank_mask:0xf
	v_fmac_f32_dpp v11, v240, v139 row_newbcast:13 row_mask:0xf bank_mask:0xf
	v_fmac_f32_dpp v12, v240, v140 row_newbcast:13 row_mask:0xf bank_mask:0xf
	v_fmac_f32_dpp v13, v240, v141 row_newbcast:13 row_mask:0xf bank_mask:0xf
	v_fmac_f32_dpp v14, v240, v142 row_newbcast:13 row_mask:0xf bank_mask:0xf
	v_fmac_f32_dpp v15, v240, v143 row_newbcast:13 row_mask:0xf bank_mask:0xf
	s_waitcnt vmcnt(2)
	v_fmac_f32_dpp v8, v240, v144 row_newbcast:14 row_mask:0xf bank_mask:0xf
	v_fmac_f32_dpp v9, v240, v145 row_newbcast:14 row_mask:0xf bank_mask:0xf
	v_fmac_f32_dpp v10, v240, v146 row_newbcast:14 row_mask:0xf bank_mask:0xf
	v_fmac_f32_dpp v11, v240, v147 row_newbcast:14 row_mask:0xf bank_mask:0xf
	v_fmac_f32_dpp v12, v240, v148 row_newbcast:14 row_mask:0xf bank_mask:0xf
	v_fmac_f32_dpp v13, v240, v149 row_newbcast:14 row_mask:0xf bank_mask:0xf
	v_fmac_f32_dpp v14, v240, v150 row_newbcast:14 row_mask:0xf bank_mask:0xf
	v_fmac_f32_dpp v15, v240, v151 row_newbcast:14 row_mask:0xf bank_mask:0xf
	s_waitcnt vmcnt(0)
	v_fmac_f32_dpp v8, v240, v152 row_newbcast:15 row_mask:0xf bank_mask:0xf
	v_fmac_f32_dpp v9, v240, v153 row_newbcast:15 row_mask:0xf bank_mask:0xf
	v_fmac_f32_dpp v10, v240, v154 row_newbcast:15 row_mask:0xf bank_mask:0xf
	v_fmac_f32_dpp v11, v240, v155 row_newbcast:15 row_mask:0xf bank_mask:0xf
	v_fmac_f32_dpp v12, v240, v156 row_newbcast:15 row_mask:0xf bank_mask:0xf
	v_fmac_f32_dpp v13, v240, v157 row_newbcast:15 row_mask:0xf bank_mask:0xf
	v_fmac_f32_dpp v14, v240, v158 row_newbcast:15 row_mask:0xf bank_mask:0xf
	v_fmac_f32_dpp v15, v240, v159 row_newbcast:15 row_mask:0xf bank_mask:0xf
	ds_bpermute_b32 v160, v238, v8
	ds_bpermute_b32 v161, v238, v9
	ds_bpermute_b32 v162, v238, v10
	ds_bpermute_b32 v163, v238, v11
	ds_bpermute_b32 v164, v238, v12
	ds_bpermute_b32 v165, v238, v13
	ds_bpermute_b32 v166, v238, v14
	ds_bpermute_b32 v167, v238, v15
	s_waitcnt lgkmcnt(0)
	v_add_f32_e32 v8, v8, v160
	v_add_f32_e32 v9, v9, v161
	v_add_f32_e32 v10, v10, v162
	v_add_f32_e32 v11, v11, v163
	v_add_f32_e32 v12, v12, v164
	v_add_f32_e32 v13, v13, v165
	v_add_f32_e32 v14, v14, v166
	v_add_f32_e32 v15, v15, v167
	ds_bpermute_b32 v160, v239, v8
	ds_bpermute_b32 v161, v239, v9
	ds_bpermute_b32 v162, v239, v10
	ds_bpermute_b32 v163, v239, v11
	ds_bpermute_b32 v164, v239, v12
	ds_bpermute_b32 v165, v239, v13
	ds_bpermute_b32 v166, v239, v14
	ds_bpermute_b32 v167, v239, v15
	s_waitcnt lgkmcnt(0)
	v_add_f32_e32 v8, v8, v160
	v_add_f32_e32 v9, v9, v161
	v_add_f32_e32 v10, v10, v162
	v_add_f32_e32 v11, v11, v163
	v_add_f32_e32 v12, v12, v164
	v_add_f32_e32 v13, v13, v165
	v_add_f32_e32 v14, v14, v166
	v_add_f32_e32 v15, v15, v167
	v_lshl_or_b32 v176, v20, 4, v18
	v_mul_u32_u24_e32 v176, 48, v176
	v_cmp_gt_u32_e32 vcc, 16, v18
	v_cmp_eq_u32_e64 s[6:7], 1, v21
	s_and_b64 s[6:7], s[6:7], vcc
	s_and_saveexec_b64 s[6:7], s[6:7]
	v_mov_b32_e32 v160, v16
	v_mov_b32_e32 v161, v17
	v_mov_b32_e32 v162, v8
	v_mov_b32_e32 v163, v9
	ds_write_b128 v176, v[160:163] offset:4096
	ds_write_b128 v176, v[10:13] offset:4112
	ds_write_b64 v176, v[14:15] offset:4128
	s_or_b64 exec, exec, s[6:7]
	s_waitcnt lgkmcnt(0)
	s_barrier
	v_cmp_gt_u32_e32 vcc, 16, v18
	v_cmp_eq_u32_e64 s[6:7], 0, v21
	s_and_b64 s[6:7], s[6:7], vcc
	s_and_saveexec_b64 s[6:7], s[6:7]
	s_cbranch_execz .Lsm1_mdone1
	global_load_dwordx4 v[172:175], v[244:245], off
	ds_read_b128 v[160:163], v176 offset:4096
	ds_read_b128 v[164:167], v176 offset:4112
	ds_read_b64 v[168:169], v176 offset:4128
	s_waitcnt lgkmcnt(0)
	v_max_f32_e32 v230, v16, v160
	v_sub_f32_e32 v231, v16, v230
	v_sub_f32_e32 v232, v160, v230
	v_mul_f32_e32 v231, 0x3fb8aa3b, v231
	v_mul_f32_e32 v232, 0x3fb8aa3b, v232
	v_exp_f32_e32 v231, v231
	v_exp_f32_e32 v232, v232
	s_nop 0
	v_mul_f32_e32 v233, v232, v161
	v_fmac_f32_e32 v233, v231, v17
	v_div_scale_f32 v234, s[8:9], v233, v233, 1.0
	v_rcp_f32_e32 v235, v234
	s_nop 0
	v_fma_f32 v236, -v234, v235, 1.0
	v_fmac_f32_e32 v235, v236, v235
	v_div_scale_f32 v236, vcc, 1.0, v233, 1.0
	v_mul_f32_e32 v237, v236, v235
	v_fma_f32 v176, -v234, v237, v236
	v_fmac_f32_e32 v237, v176, v235
	v_fma_f32 v234, -v234, v237, v236
	s_nop 0
	v_div_fmas_f32 v234, v234, v235, v237
	v_div_fixup_f32 v233, v234, v233, 1.0
	v_mul_f32_e32 v162, v232, v162
	v_fmac_f32_e32 v162, v231, v8
	v_mul_f32_e32 v162, v162, v233
	v_mul_f32_e32 v163, v232, v163
	v_fmac_f32_e32 v163, v231, v9
	v_mul_f32_e32 v163, v163, v233
	v_mul_f32_e32 v164, v232, v164
	v_fmac_f32_e32 v164, v231, v10
	v_mul_f32_e32 v164, v164, v233
	v_mul_f32_e32 v165, v232, v165
	v_fmac_f32_e32 v165, v231, v11
	v_mul_f32_e32 v165, v165, v233
	v_mul_f32_e32 v166, v232, v166
	v_fmac_f32_e32 v166, v231, v12
	v_mul_f32_e32 v166, v166, v233
	v_mul_f32_e32 v167, v232, v167
	v_fmac_f32_e32 v167, v231, v13
	v_mul_f32_e32 v167, v167, v233
	v_mul_f32_e32 v168, v232, v168
	v_fmac_f32_e32 v168, v231, v14
	v_mul_f32_e32 v168, v168, v233
	v_mul_f32_e32 v169, v232, v169
	v_fmac_f32_e32 v169, v231, v15
	v_mul_f32_e32 v169, v169, v233
	s_waitcnt vmcnt(0)
	v_lshlrev_b32_e32 v230, 16, v172
	v_and_b32_e32 v231, 0xffff0000, v172
	v_mul_f32_e32 v236, 0xbfb8aa3b, v230
	v_mul_f32_e32 v237, 0xbfb8aa3b, v231
	v_exp_f32_e32 v236, v236
	v_exp_f32_e32 v237, v237
	s_nop 0
	v_add_f32_e32 v236, 1.0, v236
	v_add_f32_e32 v237, 1.0, v237
	v_rcp_f32_e32 v236, v236
	v_rcp_f32_e32 v237, v237
	s_nop 0
	v_mul_f32_e32 v230, v230, v236
	v_mul_f32_e32 v231, v231, v237
	v_mul_f32_e32 v162, v162, v230
	v_mul_f32_e32 v163, v163, v231
	v_cvt_pk_bf16_f32 v172, v162, v163
	v_lshlrev_b32_e32 v230, 16, v173
	v_and_b32_e32 v231, 0xffff0000, v173
	v_mul_f32_e32 v236, 0xbfb8aa3b, v230
	v_mul_f32_e32 v237, 0xbfb8aa3b, v231
	v_exp_f32_e32 v236, v236
	v_exp_f32_e32 v237, v237
	s_nop 0
	v_add_f32_e32 v236, 1.0, v236
	v_add_f32_e32 v237, 1.0, v237
	v_rcp_f32_e32 v236, v236
	v_rcp_f32_e32 v237, v237
	s_nop 0
	v_mul_f32_e32 v230, v230, v236
	v_mul_f32_e32 v231, v231, v237
	v_mul_f32_e32 v164, v164, v230
	v_mul_f32_e32 v165, v165, v231
	v_cvt_pk_bf16_f32 v173, v164, v165
	v_lshlrev_b32_e32 v230, 16, v174
	v_and_b32_e32 v231, 0xffff0000, v174
	v_mul_f32_e32 v236, 0xbfb8aa3b, v230
	v_mul_f32_e32 v237, 0xbfb8aa3b, v231
	v_exp_f32_e32 v236, v236
	v_exp_f32_e32 v237, v237
	s_nop 0
	v_add_f32_e32 v236, 1.0, v236
	v_add_f32_e32 v237, 1.0, v237
	v_rcp_f32_e32 v236, v236
	v_rcp_f32_e32 v237, v237
	s_nop 0
	v_mul_f32_e32 v230, v230, v236
	v_mul_f32_e32 v231, v231, v237
	v_mul_f32_e32 v166, v166, v230
	v_mul_f32_e32 v167, v167, v231
	v_cvt_pk_bf16_f32 v174, v166, v167
	v_lshlrev_b32_e32 v230, 16, v175
	v_and_b32_e32 v231, 0xffff0000, v175
	v_mul_f32_e32 v236, 0xbfb8aa3b, v230
	v_mul_f32_e32 v237, 0xbfb8aa3b, v231
	v_exp_f32_e32 v236, v236
	v_exp_f32_e32 v237, v237
	s_nop 0
	v_add_f32_e32 v236, 1.0, v236
	v_add_f32_e32 v237, 1.0, v237
	v_rcp_f32_e32 v236, v236
	v_rcp_f32_e32 v237, v237
	s_nop 0
	v_mul_f32_e32 v230, v230, v236
	v_mul_f32_e32 v231, v231, v237
	v_mul_f32_e32 v168, v168, v230
	v_mul_f32_e32 v169, v169, v231
	v_cvt_pk_bf16_f32 v175, v168, v169
	global_store_dwordx4 v[246:247], v[172:175], off
